# split scan/attention with the two consumer waves on different SIMDs (waves 0 and 1), producers on waves 2-7
# baseline (speedup 1.0000x reference)
; __device__ __forceinline__ int obid() { int b = blockIdx.x; asm volatile("" : "+s"(b)); return b; }
; __device__ __forceinline__ void lds_barrier() { asm volatile("s_waitcnt lgkmcnt(0)" ::: "memory"); __builtin_amdgcn_s_barrier(); asm volatile("" ::: "memory"); }
; __device__ __forceinline__ void phase_scan2(const Params& p, int l, LAS unsigned char* lds) {
;     ...
;     for (int job = obid(); job < 256; job += gridDim.x) {
;         const int bh = job >> 2, rg = job & 3, b = bh >> 3, h = bh & 7;
;         const size_t tok0 = (size_t)b * SEQ;
;         const int pw = wid - 3, j = lane;
;     ...
;         if (wid >= 3) { pload(pw); pbuild(pw, lds + pw * SC_SLOT, scr, SC_NP + pw); }
;         lds_barrier();
;         for (int rd = 0; rd < NRD; ++rd) {
;             if (wid == 0) {
; #pragma unroll 1
;                 for (int q = 0; q < SC_NP; ++q) { const int c = rd * SC_NP + q; if (c < NCH) consume(c, lds + ((rd & 1) * SC_NP + q) * SC_SLOT); }
;             } else if (wid >= 3) {
;                 const int cb = (rd + 1) * SC_NP + pw, cn = cb + SC_NP;
;                 if (cb < NCH) pbuild(cb, lds + (((rd + 1) & 1) * SC_NP + pw) * SC_SLOT, scr, cn < NCH ? cn : -1);
.Lsc_job:
	s_lshr_b32 s0, s13, 4
	s_lshl_b32 s0, s0, 3
	s_and_b32 s53, s13, 7
	s_add_u32 s0, s0, s53
	s_bfe_u32 s53, s13, 0x10003
	s_lshl_b32 s53, s53, 1
	s_lshr_b32 s54, s0, 3
	s_and_b32 s52, s0, 7
	s_cmp_lt_u32 s25, 2
	s_cbranch_scc1 .Lsc_consumer
.Lsc_producer:
	s_sub_u32 s55, s25, 2
	s_cmp_gt_u32 s25, 5
	s_cbranch_scc0 .Lsc_p_noprio
	s_setprio 1

; __device__ __forceinline__ void phase_scan2(const Params& p, int l, LAS unsigned char* lds) {
;     ...
;         auto consume = [&](int c, LAS const unsigned char* sl) {
;             const bf16x8 s0 = __builtin_bit_cast(bf16x8, (u32x4){pk_bf16(ST[0][0], ST[0][1]), pk_bf16(ST[0][2], ST[0][3]), pk_bf16(ST[1][0], ST[1][1]), pk_bf16(ST[1][2], ST[1][3])});
;             const bf16x8 s1 = __builtin_bit_cast(bf16x8, (u32x4){pk_bf16(ST[2][0], ST[2][1]), pk_bf16(ST[2][2], ST[2][3]), pk_bf16(ST[3][0], ST[3][1]), pk_bf16(ST[3][2], ST[3][3])});
;             const bf16x8 at0 = *(LAS const bf16x8*)(sl + SC_AT + (fr * 32 + fq * 8) * 2), at1 = *(LAS const bf16x8*)(sl + SC_AT + ((16 + fr) * 32 + fq * 8) * 2);
;             const bf16x8 rt0 = *(LAS const bf16x8*)(sl + SC_RT + (fr * 32 + fq * 8) * 2), rt1 = *(LAS const bf16x8*)(sl + SC_RT + ((16 + fr) * 32 + fq * 8) * 2);
;             const int mo = (fr * 16 + 4 * fq) * 2;
;             const bf16x8 vf = frag4(sl + SC_VP + mo), akf = frag4(sl + SC_AK + mo), xf = frag4(sl + SC_X + mo), rbf = frag4(sl + SC_RB + mo), rkf = frag4(sl + SC_RK + mo);
;             const f32x4 z = (f32x4){0.f, 0.f, 0.f, 0.f};
;             f32x4 g = __builtin_amdgcn_mfma_f32_16x16x32_bf16(at0, s0, z, 0, 0, 0);
;             g = __builtin_amdgcn_mfma_f32_16x16x32_bf16(at1, s1, g, 0, 0, 0);
;             g = __builtin_amdgcn_mfma_f32_16x16x32_bf16(akf, vf, g, 0, 0, 0);
;             const f32x4 sa = __builtin_amdgcn_mfma_f32_16x16x32_bf16(xf, cfrag(g), z, 0, 0, 0);
;             const bf16x8 saf = cfrag(sa);
;             f32x4 y = __builtin_amdgcn_mfma_f32_16x16x32_bf16(rt0, s0, z, 0, 0, 0);
;             y = __builtin_amdgcn_mfma_f32_16x16x32_bf16(rt1, s1, y, 0, 0, 0);
;             y = __builtin_amdgcn_mfma_f32_16x16x32_bf16(rbf, saf, y, 0, 0, 0);
;             y = __builtin_amdgcn_mfma_f32_16x16x32_bf16(rkf, vf, y, 0, 0, 0);
; #pragma unroll
;             for (int jt = 0; jt < 4; ++jt) {
;                 const f32x4 wc = *(LAS const f32x4*)(sl + SC_WC + (16 * jt + 4 * fq) * 4);
;                 const bf16x8 bb = frag4(sl + SC_BBT + ((16 * jt + fr) * SC_BS + 4 * fq) * 2), kb = frag4(sl + SC_KBT + ((16 * jt + fr) * SC_BS + 4 * fq) * 2);
;                 f32x4 acc = ST[jt];
;                 acc = __builtin_amdgcn_mfma_f32_16x16x32_bf16(bb, saf, acc, 0, 0, 0);
;                 acc = __builtin_amdgcn_mfma_f32_16x16x32_bf16(kb, vf, acc, 0, 0, 0);
.Lsc_consumer:
	s_setprio 3
	v_and_b32_e32 v4, 7, v1
	s_mov_b32 s1, s25
	v_xor_b32_e32 v4, v4, v2
	s_mul_i32 s0, s1, 768
	v_lshlrev_b32_e32 v4, 4, v4
	v_and_b32_e32 v5, 3, v1
	v_lshl_add_u32 v163, v1, 7, v4
	v_lshrrev_b32_e32 v4, 2, v1
	v_add_u32_e32 v13, s0, v6
	v_lshl_add_u32 v4, v2, 2, v4
	s_add_u32 s53, s53, s1
	v_and_b32_e32 v165, 7, v4
	s_mul_i32 s0, s54, 4096
	v_xor_b32_e32 v165, v165, v5
	s_lshl_b32 s0, s0, 10
	v_lshlrev_b32_e32 v165, 4, v165
	s_lshl_b32 s14, s52, 7
	v_lshl_add_u32 v165, v4, 7, v165
	s_lshl_b32 s15, s53, 5
	s_add_u32 s0, s0, s14
	v_lshlrev_b32_e32 v164, 5, v2
	v_add_u32_e32 v165, 4096, v165
	v_lshlrev_b32_e32 v166, 12, v2
	s_add_u32 s0, s0, s15
	s_add_u32 s0, s0, 0x5000000
	v_mov_b32_e32 v8, 0
	v_mov_b32_e32 v116, 0
	v_mov_b32_e32 v9, 0
	v_mov_b32_e32 v117, 0
	v_mov_b32_e32 v10, 0
	v_mov_b32_e32 v118, 0
	v_mov_b32_e32 v11, 0
	v_mov_b32_e32 v119, 0
	v_mov_b32_e32 v16, 0
	v_mov_b32_e32 v120, 0
	v_mov_b32_e32 v17, 0
	v_mov_b32_e32 v121, 0
	v_mov_b32_e32 v18, 0
	v_mov_b32_e32 v122, 0
	v_mov_b32_e32 v19, 0
	v_mov_b32_e32 v123, 0
	v_mov_b32_e32 v20, 0
	v_mov_b32_e32 v124, 0
	v_mov_b32_e32 v21, 0
	v_mov_b32_e32 v125, 0
	v_mov_b32_e32 v22, 0
	v_mov_b32_e32 v126, 0
	v_mov_b32_e32 v23, 0
	v_mov_b32_e32 v127, 0
	v_mov_b32_e32 v24, 0
	v_mov_b32_e32 v128, 0
	v_mov_b32_e32 v25, 0
	v_mov_b32_e32 v129, 0
	v_mov_b32_e32 v26, 0
	v_mov_b32_e32 v130, 0
	v_mov_b32_e32 v27, 0
	v_mov_b32_e32 v131, 0
	v_xor_b32_e32 v169, 64, v163
	v_add_u32_e32 v164, 10752, v164
	v_xor_b32_e32 v170, 64, v165
	v_lshl_add_u32 v166, v1, 1, v166
	s_add_u32 s48, s74, s0
	s_addc_u32 s49, s75, 0
	s_mov_b32 s42, 0
	s_mov_b32 s58, 0
	s_mov_b32 s56, 0
	s_branch .Lsc_c_bar
